# third conversion tail (down2 in FFN2-gu last round), gate2 moved to in-proj tail, last 8 k-blocks of w_in moved from prologue to FFN1-gu tail (hand-written map_in path)
# speedup vs baseline: 1.0142x; 1.0109x over previous
.LBB0_29:
	v_mov_b32_e32 v16, v183
	s_cmpk_gt_i32 s4, 0x2bd7
	v_readfirstlane_b32 s3, v16
	s_cbranch_scc1 .LBB0_427
	s_cmpk_lt_i32 s4, 0xb00
	s_mov_b32 s5, 1
	s_cbranch_scc1 .LBB0_34
	s_cmpk_gt_u32 s4, 0x15ff
	s_cbranch_scc0 .LBB0_35
	v_readlane_b32 s16, v234, 40
	v_readlane_b32 s22, v234, 46
	v_readlane_b32 s23, v234, 47
	v_readlane_b32 s24, v234, 48
	v_readlane_b32 s25, v234, 49
	s_add_i32 s12, s4, 0xffffea00
	v_readlane_b32 s17, v234, 41
	v_readlane_b32 s18, v234, 42
	v_readlane_b32 s19, v234, 43
	v_readlane_b32 s20, v234, 44
	v_readlane_b32 s21, v234, 45
	v_readlane_b32 s26, v234, 50
	v_readlane_b32 s27, v234, 51
	v_readlane_b32 s28, v234, 52
	v_readlane_b32 s29, v234, 53
	v_readlane_b32 s30, v234, 54
	v_readlane_b32 s31, v234, 55
	s_mov_b64 s[8:9], s[22:23]
	s_mov_b64 s[10:11], s[24:25]
	s_cbranch_execz .LBB0_36
	s_mov_b64 s[6:7], 0x4400000
	s_movk_i32 s28, 0x3a28
	s_mov_b32 s5, 3
	s_branch .LBB0_37

.LBB0_79:
	s_add_i32 s41, s4, s50
	s_cmpk_lt_i32 s41, 0x2bd8
	s_cselect_b64 s[10:11], -1, 0
	s_cmpk_gt_i32 s41, 0x2bd7
	s_cselect_b64 s[8:9], -1, 0
	s_and_b64 vcc, exec, s[8:9]
	s_mov_b64 s[12:13], s[6:7]
	s_mov_b32 s42, s28
	s_mov_b32 s43, s5
	s_mov_b32 s44, s2
	s_mov_b32 s45, s29
	s_cbranch_vccnz .LBB0_121
	s_cmpk_lt_i32 s41, 0xb00
	s_cbranch_scc1 .LBB0_84
	s_cmpk_gt_u32 s41, 0x15ff
	s_cbranch_scc0 .LBB0_85
	v_readlane_b32 s12, v234, 40
	v_readlane_b32 s14, v234, 42
	v_readlane_b32 s15, v234, 43
	v_readlane_b32 s16, v234, 44
	v_readlane_b32 s17, v234, 45
	v_readlane_b32 s18, v234, 46
	v_readlane_b32 s19, v234, 47
	v_readlane_b32 s20, v234, 48
	v_readlane_b32 s21, v234, 49
	s_add_i32 s3, s41, 0xffffea00
	v_readlane_b32 s13, v234, 41
	v_readlane_b32 s22, v234, 50
	v_readlane_b32 s23, v234, 51
	v_readlane_b32 s24, v234, 52
	v_readlane_b32 s25, v234, 53
	v_readlane_b32 s26, v234, 54
	v_readlane_b32 s27, v234, 55
	s_mov_b64 s[14:15], s[18:19]
	s_mov_b64 s[16:17], s[20:21]
	s_cbranch_execz .LBB0_86
	s_mov_b64 s[12:13], 0x4400000
	s_movk_i32 s42, 0x3a28
	s_mov_b32 s43, 3
	s_branch .LBB0_87

.LBB0_511:
	v_readlane_b32 s0, v234, 12
	v_writelane_b32 v233, s52, 12
	s_abs_i32 s52, s0
	v_cvt_f32_u32_e32 v0, s52
	s_sub_i32 s0, 0, s52
	v_readlane_b32 s1, v234, 13
	v_writelane_b32 v233, s50, 13
	v_rcp_iflag_f32_e32 v0, v0
	s_nop 0
	v_writelane_b32 v233, s51, 14
	v_mul_f32_e32 v0, 0x4f7ffffe, v0
	v_cvt_u32_f32_e32 v0, v0
	s_nop 0
	v_readfirstlane_b32 s53, v0
	s_mul_i32 s0, s0, s53
	s_mul_hi_u32 s0, s53, s0
	s_add_i32 s53, s53, s0
	s_mul_hi_u32 s0, s53, 0x5ac
	s_mul_i32 s0, s0, s52
	s_sub_i32 s0, 0x5ac, s0
	s_sub_i32 s1, s0, s52
	s_cmp_ge_u32 s0, s52
	s_cselect_b32 s0, s1, s0
	s_sub_i32 s1, s0, s52
	s_cmp_ge_u32 s0, s52
	s_cselect_b32 s5, s1, s0
	s_cmp_eq_u32 s5, 0
	s_cselect_b64 s[0:1], -1, 0
	s_cmp_lt_i32 s4, s5
	s_cselect_b64 s[2:3], -1, 0
	s_or_b64 s[0:1], s[0:1], s[2:3]
	s_and_b64 vcc, exec, s[0:1]
	s_cbranch_vccnz .LBB0_931
	v_readlane_b32 s2, v234, 14
	v_readlane_b32 s3, v234, 12
	v_readfirstlane_b32 s0, v183
	s_sub_i32 s2, s2, s5
	s_sub_i32 s3, s3, s5
	s_lshl_b32 s2, s2, 3
	s_lshr_b32 s0, s0, 6
	s_add_i32 s4, s2, s0
	s_lshl_b32 s33, s3, 3
	s_cmp_ge_u32 s4, 0x1248
	s_cbranch_scc1 .LBB0_931
	v_readlane_b32 s30, v234, 2
	v_readlane_b32 s31, v234, 3
	v_and_b32_e32 v176, 7, v183
	v_bfe_u32 v185, v183, 3, 3
	v_lshlrev_b32_e32 v177, 4, v185
	v_lshlrev_b32_e32 v186, 4, v176
	s_cmp_lt_u32 s4, 0x1248
	s_cbranch_scc1 .Lcv1_p0_go
	s_mov_b32 s22, 0
	s_branch .Lcv1_p0_end
.Lcv1_p0_go:
	s_cmp_lt_u32 s4, 0xb00
	s_cbranch_scc0 .Lcv1_p0_seg1
	s_add_u32 s34, s4, 0x0
	s_lshr_b32 s39, s34, 5
	s_and_b32 s40, s34, 31
	v_readlane_b32 s0, v234, 44
	v_readlane_b32 s1, v234, 45
	s_mul_i32 s2, s39, 0x80000
	s_lshl_b32 s3, s40, 8
	s_add_u32 s2, s2, s3
	s_add_u32 s0, s0, s2
	s_addc_u32 s1, s1, 0
	s_mov_b32 s41, 0x2000
	s_mov_b32 s42, 0x10000
	s_mul_i32 s2, s40, 0xb0000
	s_lshl_b32 s3, s39, 7
	s_add_u32 s2, s2, s3
	s_add_u32 s2, s2, 0x2e00000
	s_add_u32 s16, s30, s2
	s_addc_u32 s17, s31, 0
	s_mov_b32 s20, 0x2c00
	s_mov_b32 s21, 0xb000
	s_mov_b32 s23, -1
	s_mov_b32 s22, 16
	s_branch .Lcv1_p0_ld
.Lcv1_p0_seg1:
	s_add_u32 s34, s4, 0xad8
	s_mul_i32 s39, s34, 18002
	s_lshr_b32 s39, s39, 22
	s_mul_i32 s40, s39, 233
	s_sub_u32 s40, s34, s40
	v_readlane_b32 s0, v234, 48
	v_readlane_b32 s1, v234, 49
	s_mul_i32 s2, s39, 0x3a2800
	s_lshl_b32 s3, s40, 8
	s_add_u32 s2, s2, s3
	s_add_u32 s0, s0, s2
	s_addc_u32 s1, s1, 0
	s_mov_b32 s41, 0xe8a0
	s_mov_b32 s42, 0x74500
	s_lshl_b32 s2, s40, 18
	s_lshl_b32 s3, s39, 7
	s_add_u32 s2, s2, s3
	s_add_u32 s2, s2, 0x43d8000
	s_add_u32 s16, s30, s2
	s_addc_u32 s17, s31, 0
	s_mov_b32 s20, 0x1000
	s_mov_b32 s21, 0x4000
	s_lshl_b32 s23, s40, 6
	s_mov_b64 s[46:47], -1
	s_cmp_eq_u32 s40, 232
	s_cbranch_scc0 .Lcv1_p0_full1
	s_mov_b64 s[46:47], 0xffff
.Lcv1_p0_full1:
	v_readlane_b32 s8, v234, 46
	v_readlane_b32 s9, v234, 47
	s_lshl_b32 s3, s39, 8
	s_mov_b32 s22, 18
	s_nop 0
	s_add_u32 s8, s8, s3
	s_addc_u32 s9, s9, 0
	v_mad_u32_u24 v178, v176, s42, v177
	s_mov_b64 s[2:3], s[0:1]
	global_load_dwordx4 v[0:3], v178, s[0:1] nt
	s_add_u32 s0, s0, s41
	s_addc_u32 s1, s1, 0
	global_load_dwordx4 v[8:11], v178, s[0:1] nt
	s_add_u32 s0, s0, s41
	s_addc_u32 s1, s1, 0
	global_load_dwordx4 v[16:19], v178, s[0:1] nt
	s_add_u32 s0, s0, s41
	s_addc_u32 s1, s1, 0
	global_load_dwordx4 v[24:27], v178, s[0:1] nt
	s_add_u32 s0, s0, s41
	s_addc_u32 s1, s1, 0
	global_load_dwordx4 v[32:35], v178, s[0:1] nt
	s_add_u32 s0, s0, s41
	s_addc_u32 s1, s1, 0
	global_load_dwordx4 v[40:43], v178, s[0:1] nt
	s_add_u32 s0, s0, s41
	s_addc_u32 s1, s1, 0
	global_load_dwordx4 v[48:51], v178, s[0:1] nt
	s_add_u32 s0, s0, s41
	s_addc_u32 s1, s1, 0
	global_load_dwordx4 v[56:59], v178, s[0:1] nt
	s_mov_b64 exec, s[46:47]
	global_load_dwordx4 v[4:7], v178, s[2:3] offset:128 nt
	s_add_u32 s2, s2, s41
	s_addc_u32 s3, s3, 0
	global_load_dwordx4 v[12:15], v178, s[2:3] offset:128 nt
	s_add_u32 s2, s2, s41
	s_addc_u32 s3, s3, 0
	global_load_dwordx4 v[20:23], v178, s[2:3] offset:128 nt
	s_add_u32 s2, s2, s41
	s_addc_u32 s3, s3, 0
	global_load_dwordx4 v[28:31], v178, s[2:3] offset:128 nt
	s_add_u32 s2, s2, s41
	s_addc_u32 s3, s3, 0
	global_load_dwordx4 v[36:39], v178, s[2:3] offset:128 nt
	s_add_u32 s2, s2, s41
	s_addc_u32 s3, s3, 0
	global_load_dwordx4 v[44:47], v178, s[2:3] offset:128 nt
	s_add_u32 s2, s2, s41
	s_addc_u32 s3, s3, 0
	global_load_dwordx4 v[52:55], v178, s[2:3] offset:128 nt
	s_add_u32 s2, s2, s41
	s_addc_u32 s3, s3, 0
	global_load_dwordx4 v[60:63], v178, s[2:3] offset:128 nt
	s_mov_b64 exec, -1
	s_branch .Lcv1_p0_kw

.Lcv1_p0_kw:
	s_cmp_eq_u32 s22, 18
	s_cbranch_scc0 .Lcv1_p0_nokw
	v_lshlrev_b32_e32 v178, 5, v176
	global_load_dwordx4 v[128:131], v178, s[8:9]
	global_load_dwordx4 v[132:135], v178, s[8:9] offset:16
	s_branch .Lcv1_p0_kwd

.Lcv1_p0_end:
	s_cmp_lt_u32 s4, 0x1248
	s_cbranch_scc1 .Lcv1_p1_go
	s_mov_b32 s28, 0
	s_branch .Lcv1_p1_end
.Lcv1_p1_go:
	s_cmp_lt_u32 s4, 0xb00
	s_cbranch_scc0 .Lcv1_p1_seg1
	s_add_u32 s34, s4, 0x0
	s_lshr_b32 s39, s34, 5
	s_and_b32 s40, s34, 31
	v_readlane_b32 s0, v234, 44
	v_readlane_b32 s1, v234, 45
	s_mul_i32 s2, s39, 0x80000
	s_lshl_b32 s3, s40, 8
	s_add_u32 s2, s2, s3
	s_add_u32 s0, s0, s2
	s_addc_u32 s1, s1, 0
	s_mov_b32 s41, 0x2000
	s_mov_b32 s42, 0x10000
	s_mul_i32 s2, s40, 0xb0000
	s_lshl_b32 s3, s39, 7
	s_add_u32 s2, s2, s3
	s_add_u32 s2, s2, 0x2e00000
	s_add_u32 s24, s30, s2
	s_addc_u32 s25, s31, 0
	s_mov_b32 s26, 0x2c00
	s_mov_b32 s27, 0xb000
	s_mov_b32 s29, -1
	s_mov_b32 s28, 16
	s_branch .Lcv1_p1_ld
.Lcv1_p1_seg1:
	s_add_u32 s34, s4, 0xad8
	s_mul_i32 s39, s34, 18002
	s_lshr_b32 s39, s39, 22
	s_mul_i32 s40, s39, 233
	s_sub_u32 s40, s34, s40
	v_readlane_b32 s0, v234, 48
	v_readlane_b32 s1, v234, 49
	s_mul_i32 s2, s39, 0x3a2800
	s_lshl_b32 s3, s40, 8
	s_add_u32 s2, s2, s3
	s_add_u32 s0, s0, s2
	s_addc_u32 s1, s1, 0
	s_mov_b32 s41, 0xe8a0
	s_mov_b32 s42, 0x74500
	s_lshl_b32 s2, s40, 18
	s_lshl_b32 s3, s39, 7
	s_add_u32 s2, s2, s3
	s_add_u32 s2, s2, 0x43d8000
	s_add_u32 s24, s30, s2
	s_addc_u32 s25, s31, 0
	s_mov_b32 s26, 0x1000
	s_mov_b32 s27, 0x4000
	s_lshl_b32 s29, s40, 6
	s_mov_b64 s[46:47], -1
	s_cmp_eq_u32 s40, 232
	s_cbranch_scc0 .Lcv1_p1_full1
	s_mov_b64 s[46:47], 0xffff
.Lcv1_p1_full1:
	v_readlane_b32 s8, v234, 46
	v_readlane_b32 s9, v234, 47
	s_lshl_b32 s3, s39, 8
	s_mov_b32 s28, 18
	s_nop 0
	s_add_u32 s8, s8, s3
	s_addc_u32 s9, s9, 0
	v_mad_u32_u24 v178, v176, s42, v177
	s_mov_b64 s[2:3], s[0:1]
	global_load_dwordx4 v[64:67], v178, s[0:1] nt
	s_add_u32 s0, s0, s41
	s_addc_u32 s1, s1, 0
	global_load_dwordx4 v[72:75], v178, s[0:1] nt
	s_add_u32 s0, s0, s41
	s_addc_u32 s1, s1, 0
	global_load_dwordx4 v[80:83], v178, s[0:1] nt
	s_add_u32 s0, s0, s41
	s_addc_u32 s1, s1, 0
	global_load_dwordx4 v[88:91], v178, s[0:1] nt
	s_add_u32 s0, s0, s41
	s_addc_u32 s1, s1, 0
	global_load_dwordx4 v[96:99], v178, s[0:1] nt
	s_add_u32 s0, s0, s41
	s_addc_u32 s1, s1, 0
	global_load_dwordx4 v[104:107], v178, s[0:1] nt
	s_add_u32 s0, s0, s41
	s_addc_u32 s1, s1, 0
	global_load_dwordx4 v[112:115], v178, s[0:1] nt
	s_add_u32 s0, s0, s41
	s_addc_u32 s1, s1, 0
	global_load_dwordx4 v[120:123], v178, s[0:1] nt
	s_mov_b64 exec, s[46:47]
	global_load_dwordx4 v[68:71], v178, s[2:3] offset:128 nt
	s_add_u32 s2, s2, s41
	s_addc_u32 s3, s3, 0
	global_load_dwordx4 v[76:79], v178, s[2:3] offset:128 nt
	s_add_u32 s2, s2, s41
	s_addc_u32 s3, s3, 0
	global_load_dwordx4 v[84:87], v178, s[2:3] offset:128 nt
	s_add_u32 s2, s2, s41
	s_addc_u32 s3, s3, 0
	global_load_dwordx4 v[92:95], v178, s[2:3] offset:128 nt
	s_add_u32 s2, s2, s41
	s_addc_u32 s3, s3, 0
	global_load_dwordx4 v[100:103], v178, s[2:3] offset:128 nt
	s_add_u32 s2, s2, s41
	s_addc_u32 s3, s3, 0
	global_load_dwordx4 v[108:111], v178, s[2:3] offset:128 nt
	s_add_u32 s2, s2, s41
	s_addc_u32 s3, s3, 0
	global_load_dwordx4 v[116:119], v178, s[2:3] offset:128 nt
	s_add_u32 s2, s2, s41
	s_addc_u32 s3, s3, 0
	global_load_dwordx4 v[124:127], v178, s[2:3] offset:128 nt
	s_mov_b64 exec, -1
	s_branch .Lcv1_p1_kw

.Lcv1_p1_kw:
	s_cmp_eq_u32 s28, 18
	s_cbranch_scc0 .Lcv1_p1_nokw
	v_lshlrev_b32_e32 v178, 5, v176
	global_load_dwordx4 v[136:139], v178, s[8:9]
	global_load_dwordx4 v[140:143], v178, s[8:9] offset:16
	s_branch .Lcv1_p1_kwd

.Lcv1_pw_wd:
.Lcv1_loop:
	v_mad_u32_u24 v179, v185, s21, v186
	s_mov_b64 s[48:49], -1
	v_mov_b32_e32 v184, v179
	s_cmp_eq_u32 s23, -1
	s_cbranch_scc1 .Lcv1_pa_plain
	s_add_u32 s2, s23, 0
	v_lshrrev_b32_e32 v147, 2, v177
	v_add_u32_e32 v147, s2, v147
	v_mov_b32_e32 v144, 40
	v_cmp_le_u32_e32 vcc, 0x1000, v147
	s_mov_b32 s3, 10752
	v_cndmask_b32_e64 v146, 0, 1, vcc
	v_mad_i32_i24 v144, v146, s3, v144
	v_cmp_le_u32_e32 vcc, 0x1008, v147
	s_mov_b32 s3, -10760
	v_cndmask_b32_e64 v146, 0, 1, vcc
	v_mad_i32_i24 v144, v146, s3, v144
	v_cmp_le_u32_e32 vcc, 0x2a08, v147
	s_mov_b32 s3, 4104
	v_cndmask_b32_e64 v146, 0, 1, vcc
	v_mad_i32_i24 v144, v146, s3, v144
	v_cmp_le_u32_e32 vcc, 0x2a28, v147
	s_mov_b32 s3, -4136
	v_cndmask_b32_e64 v146, 0, 1, vcc
	v_mad_i32_i24 v144, v146, s3, v144
	s_add_u32 s2, s23, 32
	v_lshrrev_b32_e32 v147, 2, v177
	v_add_u32_e32 v147, s2, v147
	v_mov_b32_e32 v145, 40
	v_cmp_le_u32_e32 vcc, 0x1000, v147
	s_mov_b32 s3, 10752
	v_cndmask_b32_e64 v146, 0, 1, vcc
	v_mad_i32_i24 v145, v146, s3, v145
	v_cmp_le_u32_e32 vcc, 0x1008, v147
	s_mov_b32 s3, -10760
	v_cndmask_b32_e64 v146, 0, 1, vcc
	v_mad_i32_i24 v145, v146, s3, v145
	v_cmp_le_u32_e32 vcc, 0x2a08, v147
	s_mov_b32 s3, 4104
	v_cndmask_b32_e64 v146, 0, 1, vcc
	v_mad_i32_i24 v145, v146, s3, v145
	v_cmp_le_u32_e32 vcc, 0x2a28, v147
	s_mov_b32 s3, -4136
	v_cndmask_b32_e64 v146, 0, 1, vcc
	v_mad_i32_i24 v145, v146, s3, v145
	v_lshl_add_u32 v184, v145, 12, v179
	v_lshl_add_u32 v179, v144, 12, v179
	s_cmp_lt_u32 s23, 0x400
	s_cbranch_scc0 .Lcv1_pa_nosc
	v_mul_f32_e32 v128, 0x3d800000, v128
	v_mul_f32_e32 v129, 0x3d800000, v129
	v_mul_f32_e32 v130, 0x3d800000, v130
	v_mul_f32_e32 v131, 0x3d800000, v131
	v_mul_f32_e32 v132, 0x3d800000, v132
	v_mul_f32_e32 v133, 0x3d800000, v133
	v_mul_f32_e32 v134, 0x3d800000, v134
	v_mul_f32_e32 v135, 0x3d800000, v135
.Lcv1_pa_nosc:
	s_cmp_eq_u32 s23, 0x3a00
	s_cbranch_scc0 .Lcv1_pa_plain
	s_mov_b64 s[48:49], 0xffff
.Lcv1_pa_plain:
	v_pk_mul_f32 v[0:1], v[0:1], v[128:129] op_sel_hi:[1,0]
	v_pk_mul_f32 v[2:3], v[2:3], v[128:129] op_sel_hi:[1,0]
	v_pk_mul_f32 v[4:5], v[4:5], v[128:129] op_sel_hi:[1,0]
	v_pk_mul_f32 v[6:7], v[6:7], v[128:129] op_sel_hi:[1,0]
	v_pk_mul_f32 v[8:9], v[8:9], v[128:129] op_sel:[0,1]
	v_pk_mul_f32 v[10:11], v[10:11], v[128:129] op_sel:[0,1]
	v_pk_mul_f32 v[12:13], v[12:13], v[128:129] op_sel:[0,1]
	v_pk_mul_f32 v[14:15], v[14:15], v[128:129] op_sel:[0,1]
	v_pk_mul_f32 v[16:17], v[16:17], v[130:131] op_sel_hi:[1,0]
	v_pk_mul_f32 v[18:19], v[18:19], v[130:131] op_sel_hi:[1,0]
	v_pk_mul_f32 v[20:21], v[20:21], v[130:131] op_sel_hi:[1,0]
	v_pk_mul_f32 v[22:23], v[22:23], v[130:131] op_sel_hi:[1,0]
	v_pk_mul_f32 v[24:25], v[24:25], v[130:131] op_sel:[0,1]
	v_pk_mul_f32 v[26:27], v[26:27], v[130:131] op_sel:[0,1]
	v_pk_mul_f32 v[28:29], v[28:29], v[130:131] op_sel:[0,1]
	v_pk_mul_f32 v[30:31], v[30:31], v[130:131] op_sel:[0,1]
	v_pk_mul_f32 v[32:33], v[32:33], v[132:133] op_sel_hi:[1,0]
	v_pk_mul_f32 v[34:35], v[34:35], v[132:133] op_sel_hi:[1,0]
	v_pk_mul_f32 v[36:37], v[36:37], v[132:133] op_sel_hi:[1,0]
	v_pk_mul_f32 v[38:39], v[38:39], v[132:133] op_sel_hi:[1,0]
	v_pk_mul_f32 v[40:41], v[40:41], v[132:133] op_sel:[0,1]
	v_pk_mul_f32 v[42:43], v[42:43], v[132:133] op_sel:[0,1]
	v_pk_mul_f32 v[44:45], v[44:45], v[132:133] op_sel:[0,1]
	v_pk_mul_f32 v[46:47], v[46:47], v[132:133] op_sel:[0,1]
	v_pk_mul_f32 v[48:49], v[48:49], v[134:135] op_sel_hi:[1,0]
	v_pk_mul_f32 v[50:51], v[50:51], v[134:135] op_sel_hi:[1,0]
	v_pk_mul_f32 v[52:53], v[52:53], v[134:135] op_sel_hi:[1,0]
	v_pk_mul_f32 v[54:55], v[54:55], v[134:135] op_sel_hi:[1,0]
	v_pk_mul_f32 v[56:57], v[56:57], v[134:135] op_sel:[0,1]
	v_pk_mul_f32 v[58:59], v[58:59], v[134:135] op_sel:[0,1]
	v_pk_mul_f32 v[60:61], v[60:61], v[134:135] op_sel:[0,1]
	v_pk_mul_f32 v[62:63], v[62:63], v[134:135] op_sel:[0,1]
	v_cvt_pk_bf16_f32 v144, v0, v8
	v_cvt_pk_bf16_f32 v145, v16, v24
	v_cvt_pk_bf16_f32 v146, v32, v40
	v_cvt_pk_bf16_f32 v147, v48, v56
	global_store_dwordx4 v179, v[144:147], s[16:17]
	v_cvt_pk_bf16_f32 v148, v1, v9
	v_cvt_pk_bf16_f32 v149, v17, v25
	v_cvt_pk_bf16_f32 v150, v33, v41
	v_cvt_pk_bf16_f32 v151, v49, v57
	s_add_u32 s16, s16, s20
	s_addc_u32 s17, s17, 0
	global_store_dwordx4 v179, v[148:151], s[16:17]
	v_cvt_pk_bf16_f32 v152, v2, v10
	v_cvt_pk_bf16_f32 v153, v18, v26
	v_cvt_pk_bf16_f32 v154, v34, v42
	v_cvt_pk_bf16_f32 v155, v50, v58
	s_add_u32 s16, s16, s20
	s_addc_u32 s17, s17, 0
	global_store_dwordx4 v179, v[152:155], s[16:17]
	v_cvt_pk_bf16_f32 v156, v3, v11
	v_cvt_pk_bf16_f32 v157, v19, v27
	v_cvt_pk_bf16_f32 v158, v35, v43
	v_cvt_pk_bf16_f32 v159, v51, v59
	s_add_u32 s16, s16, s20
	s_addc_u32 s17, s17, 0
	global_store_dwordx4 v179, v[156:159], s[16:17]
	s_mov_b64 exec, s[48:49]
	v_cvt_pk_bf16_f32 v160, v4, v12
	v_cvt_pk_bf16_f32 v161, v20, v28
	v_cvt_pk_bf16_f32 v162, v36, v44
	v_cvt_pk_bf16_f32 v163, v52, v60
	s_mul_i32 s2, s20, 29
	s_add_u32 s16, s16, s2
	s_addc_u32 s17, s17, 0
	global_store_dwordx4 v184, v[160:163], s[16:17]
	v_cvt_pk_bf16_f32 v164, v5, v13
	v_cvt_pk_bf16_f32 v165, v21, v29
	v_cvt_pk_bf16_f32 v166, v37, v45
	v_cvt_pk_bf16_f32 v167, v53, v61
	s_add_u32 s16, s16, s20
	s_addc_u32 s17, s17, 0
	global_store_dwordx4 v184, v[164:167], s[16:17]
	v_cvt_pk_bf16_f32 v168, v6, v14
	v_cvt_pk_bf16_f32 v169, v22, v30
	v_cvt_pk_bf16_f32 v170, v38, v46
	v_cvt_pk_bf16_f32 v171, v54, v62
	s_add_u32 s16, s16, s20
	s_addc_u32 s17, s17, 0
	global_store_dwordx4 v184, v[168:171], s[16:17]
	v_cvt_pk_bf16_f32 v172, v7, v15
	v_cvt_pk_bf16_f32 v173, v23, v31
	v_cvt_pk_bf16_f32 v174, v39, v47
	v_cvt_pk_bf16_f32 v175, v55, v63
	s_add_u32 s16, s16, s20
	s_addc_u32 s17, s17, 0
	global_store_dwordx4 v184, v[172:175], s[16:17]
	s_mov_b64 exec, -1
	s_cmp_lt_u32 s4, 0x1248
	s_cbranch_scc1 .Lcv1_la_go
	s_mov_b32 s22, 0
	s_branch .Lcv1_la_end

.Lcv1_wb_wd:
	v_mad_u32_u24 v179, v185, s27, v186
	s_mov_b64 s[48:49], -1
	v_mov_b32_e32 v184, v179
	s_cmp_eq_u32 s29, -1
	s_cbranch_scc1 .Lcv1_pb_plain
	s_add_u32 s2, s29, 0
	v_lshrrev_b32_e32 v147, 2, v177
	v_add_u32_e32 v147, s2, v147
	v_mov_b32_e32 v144, 40
	v_cmp_le_u32_e32 vcc, 0x1000, v147
	s_mov_b32 s3, 10752
	v_cndmask_b32_e64 v146, 0, 1, vcc
	v_mad_i32_i24 v144, v146, s3, v144
	v_cmp_le_u32_e32 vcc, 0x1008, v147
	s_mov_b32 s3, -10760
	v_cndmask_b32_e64 v146, 0, 1, vcc
	v_mad_i32_i24 v144, v146, s3, v144
	v_cmp_le_u32_e32 vcc, 0x2a08, v147
	s_mov_b32 s3, 4104
	v_cndmask_b32_e64 v146, 0, 1, vcc
	v_mad_i32_i24 v144, v146, s3, v144
	v_cmp_le_u32_e32 vcc, 0x2a28, v147
	s_mov_b32 s3, -4136
	v_cndmask_b32_e64 v146, 0, 1, vcc
	v_mad_i32_i24 v144, v146, s3, v144
	s_add_u32 s2, s29, 32
	v_lshrrev_b32_e32 v147, 2, v177
	v_add_u32_e32 v147, s2, v147
	v_mov_b32_e32 v145, 40
	v_cmp_le_u32_e32 vcc, 0x1000, v147
	s_mov_b32 s3, 10752
	v_cndmask_b32_e64 v146, 0, 1, vcc
	v_mad_i32_i24 v145, v146, s3, v145
	v_cmp_le_u32_e32 vcc, 0x1008, v147
	s_mov_b32 s3, -10760
	v_cndmask_b32_e64 v146, 0, 1, vcc
	v_mad_i32_i24 v145, v146, s3, v145
	v_cmp_le_u32_e32 vcc, 0x2a08, v147
	s_mov_b32 s3, 4104
	v_cndmask_b32_e64 v146, 0, 1, vcc
	v_mad_i32_i24 v145, v146, s3, v145
	v_cmp_le_u32_e32 vcc, 0x2a28, v147
	s_mov_b32 s3, -4136
	v_cndmask_b32_e64 v146, 0, 1, vcc
	v_mad_i32_i24 v145, v146, s3, v145
	v_lshl_add_u32 v184, v145, 12, v179
	v_lshl_add_u32 v179, v144, 12, v179
	s_cmp_lt_u32 s29, 0x400
	s_cbranch_scc0 .Lcv1_pb_nosc
	v_mul_f32_e32 v136, 0x3d800000, v136
	v_mul_f32_e32 v137, 0x3d800000, v137
	v_mul_f32_e32 v138, 0x3d800000, v138
	v_mul_f32_e32 v139, 0x3d800000, v139
	v_mul_f32_e32 v140, 0x3d800000, v140
	v_mul_f32_e32 v141, 0x3d800000, v141
	v_mul_f32_e32 v142, 0x3d800000, v142
	v_mul_f32_e32 v143, 0x3d800000, v143
.Lcv1_pb_nosc:
	s_cmp_eq_u32 s29, 0x3a00
	s_cbranch_scc0 .Lcv1_pb_plain
	s_mov_b64 s[48:49], 0xffff
.Lcv1_pb_plain:
	v_pk_mul_f32 v[64:65], v[64:65], v[136:137] op_sel_hi:[1,0]
	v_pk_mul_f32 v[66:67], v[66:67], v[136:137] op_sel_hi:[1,0]
	v_pk_mul_f32 v[68:69], v[68:69], v[136:137] op_sel_hi:[1,0]
	v_pk_mul_f32 v[70:71], v[70:71], v[136:137] op_sel_hi:[1,0]
	v_pk_mul_f32 v[72:73], v[72:73], v[136:137] op_sel:[0,1]
	v_pk_mul_f32 v[74:75], v[74:75], v[136:137] op_sel:[0,1]
	v_pk_mul_f32 v[76:77], v[76:77], v[136:137] op_sel:[0,1]
	v_pk_mul_f32 v[78:79], v[78:79], v[136:137] op_sel:[0,1]
	v_pk_mul_f32 v[80:81], v[80:81], v[138:139] op_sel_hi:[1,0]
	v_pk_mul_f32 v[82:83], v[82:83], v[138:139] op_sel_hi:[1,0]
	v_pk_mul_f32 v[84:85], v[84:85], v[138:139] op_sel_hi:[1,0]
	v_pk_mul_f32 v[86:87], v[86:87], v[138:139] op_sel_hi:[1,0]
	v_pk_mul_f32 v[88:89], v[88:89], v[138:139] op_sel:[0,1]
	v_pk_mul_f32 v[90:91], v[90:91], v[138:139] op_sel:[0,1]
	v_pk_mul_f32 v[92:93], v[92:93], v[138:139] op_sel:[0,1]
	v_pk_mul_f32 v[94:95], v[94:95], v[138:139] op_sel:[0,1]
	v_pk_mul_f32 v[96:97], v[96:97], v[140:141] op_sel_hi:[1,0]
	v_pk_mul_f32 v[98:99], v[98:99], v[140:141] op_sel_hi:[1,0]
	v_pk_mul_f32 v[100:101], v[100:101], v[140:141] op_sel_hi:[1,0]
	v_pk_mul_f32 v[102:103], v[102:103], v[140:141] op_sel_hi:[1,0]
	v_pk_mul_f32 v[104:105], v[104:105], v[140:141] op_sel:[0,1]
	v_pk_mul_f32 v[106:107], v[106:107], v[140:141] op_sel:[0,1]
	v_pk_mul_f32 v[108:109], v[108:109], v[140:141] op_sel:[0,1]
	v_pk_mul_f32 v[110:111], v[110:111], v[140:141] op_sel:[0,1]
	v_pk_mul_f32 v[112:113], v[112:113], v[142:143] op_sel_hi:[1,0]
	v_pk_mul_f32 v[114:115], v[114:115], v[142:143] op_sel_hi:[1,0]
	v_pk_mul_f32 v[116:117], v[116:117], v[142:143] op_sel_hi:[1,0]
	v_pk_mul_f32 v[118:119], v[118:119], v[142:143] op_sel_hi:[1,0]
	v_pk_mul_f32 v[120:121], v[120:121], v[142:143] op_sel:[0,1]
	v_pk_mul_f32 v[122:123], v[122:123], v[142:143] op_sel:[0,1]
	v_pk_mul_f32 v[124:125], v[124:125], v[142:143] op_sel:[0,1]
	v_pk_mul_f32 v[126:127], v[126:127], v[142:143] op_sel:[0,1]
	v_cvt_pk_bf16_f32 v144, v64, v72
	v_cvt_pk_bf16_f32 v145, v80, v88
	v_cvt_pk_bf16_f32 v146, v96, v104
	v_cvt_pk_bf16_f32 v147, v112, v120
	global_store_dwordx4 v179, v[144:147], s[24:25]
	v_cvt_pk_bf16_f32 v148, v65, v73
	v_cvt_pk_bf16_f32 v149, v81, v89
	v_cvt_pk_bf16_f32 v150, v97, v105
	v_cvt_pk_bf16_f32 v151, v113, v121
	s_add_u32 s24, s24, s26
	s_addc_u32 s25, s25, 0
	global_store_dwordx4 v179, v[148:151], s[24:25]
	v_cvt_pk_bf16_f32 v152, v66, v74
	v_cvt_pk_bf16_f32 v153, v82, v90
	v_cvt_pk_bf16_f32 v154, v98, v106
	v_cvt_pk_bf16_f32 v155, v114, v122
	s_add_u32 s24, s24, s26
	s_addc_u32 s25, s25, 0
	global_store_dwordx4 v179, v[152:155], s[24:25]
	v_cvt_pk_bf16_f32 v156, v67, v75
	v_cvt_pk_bf16_f32 v157, v83, v91
	v_cvt_pk_bf16_f32 v158, v99, v107
	v_cvt_pk_bf16_f32 v159, v115, v123
	s_add_u32 s24, s24, s26
	s_addc_u32 s25, s25, 0
	global_store_dwordx4 v179, v[156:159], s[24:25]
	s_mov_b64 exec, s[48:49]
	v_cvt_pk_bf16_f32 v160, v68, v76
	v_cvt_pk_bf16_f32 v161, v84, v92
	v_cvt_pk_bf16_f32 v162, v100, v108
	v_cvt_pk_bf16_f32 v163, v116, v124
	s_mul_i32 s2, s26, 29
	s_add_u32 s24, s24, s2
	s_addc_u32 s25, s25, 0
	global_store_dwordx4 v184, v[160:163], s[24:25]
	v_cvt_pk_bf16_f32 v164, v69, v77
	v_cvt_pk_bf16_f32 v165, v85, v93
	v_cvt_pk_bf16_f32 v166, v101, v109
	v_cvt_pk_bf16_f32 v167, v117, v125
	s_add_u32 s24, s24, s26
	s_addc_u32 s25, s25, 0
	global_store_dwordx4 v184, v[164:167], s[24:25]
	v_cvt_pk_bf16_f32 v168, v70, v78
	v_cvt_pk_bf16_f32 v169, v86, v94
	v_cvt_pk_bf16_f32 v170, v102, v110
	v_cvt_pk_bf16_f32 v171, v118, v126
	s_add_u32 s24, s24, s26
	s_addc_u32 s25, s25, 0
	global_store_dwordx4 v184, v[168:171], s[24:25]
	v_cvt_pk_bf16_f32 v172, v71, v79
	v_cvt_pk_bf16_f32 v173, v87, v95
	v_cvt_pk_bf16_f32 v174, v103, v111
	v_cvt_pk_bf16_f32 v175, v119, v127
	s_add_u32 s24, s24, s26
	s_addc_u32 s25, s25, 0
	global_store_dwordx4 v184, v[172:175], s[24:25]
	s_mov_b64 exec, -1
	s_cmp_lt_u32 s4, 0x1248
	s_cbranch_scc1 .Lcv1_lb_go
	s_mov_b32 s28, 0
	s_branch .Lcv1_lb_end

.LBB0_1169:
	s_mul_hi_u32 s0, s53, 0x79b
	s_mul_i32 s0, s0, s52
	s_sub_i32 s0, 0x79b, s0
	s_sub_i32 s1, s0, s52
	s_cmp_ge_u32 s0, s52
	s_cselect_b32 s0, s1, s0
	s_sub_i32 s1, s0, s52
	s_cmp_ge_u32 s0, s52
	s_cselect_b32 s7, s1, s0
	s_cmp_lg_u32 s7, 0
	v_readlane_b32 s2, v234, 14
	s_cselect_b64 s[0:1], -1, 0
	s_cmp_ge_i32 s2, s7
	s_cselect_b64 s[2:3], -1, 0
	s_and_b64 s[0:1], s[0:1], s[2:3]
	s_and_b64 vcc, exec, s[0:1]
	s_cbranch_vccz .LBB0_1605
	v_readlane_b32 s2, v234, 14
	v_readlane_b32 s3, v234, 12
	v_readfirstlane_b32 s0, v183
	s_sub_i32 s2, s2, s7
	s_sub_i32 s3, s3, s7
	s_lshl_b32 s2, s2, 3
	s_lshr_b32 s0, s0, 6
	s_add_i32 s4, s2, s0
	s_lshl_b32 s33, s3, 3
	s_cmp_ge_u32 s4, 0x1a00
	s_cbranch_scc1 .LBB0_1605
	v_readlane_b32 s30, v234, 2
	v_readlane_b32 s31, v234, 3
	v_and_b32_e32 v176, 7, v183
	v_bfe_u32 v185, v183, 3, 3
	v_lshlrev_b32_e32 v177, 4, v185
	v_lshlrev_b32_e32 v186, 4, v176
	s_cmp_lt_u32 s4, 0x1a00
	s_cbranch_scc1 .Lcv2_p0_go
	s_mov_b32 s22, 0
	s_branch .Lcv2_p0_end
.Lcv2_p0_go:
	s_cmp_lt_u32 s4, 0x400
	s_cbranch_scc0 .Lcv2_p0_seg1
	s_add_u32 s34, s4, 0x0
	s_lshr_b32 s39, s34, 5
	s_and_b32 s40, s34, 31
	v_readlane_b32 s0, v233, 4
	v_readlane_b32 s1, v233, 5
	s_mul_i32 s2, s39, 0x80000
	s_lshl_b32 s3, s40, 8
	s_add_u32 s2, s2, s3
	s_add_u32 s0, s0, s2
	s_addc_u32 s1, s1, 0
	s_mov_b32 s41, 0x2000
	s_mov_b32 s42, 0x10000
	s_mul_i32 s2, s40, 0x40000
	s_lshl_b32 s3, s39, 7
	s_add_u32 s2, s2, s3
	s_add_u32 s2, s2, 0x7f00000
	s_add_u32 s16, s30, s2
	s_addc_u32 s17, s31, 0
	s_mov_b32 s20, 0x1000
	s_mov_b32 s21, 0x4000
	s_mov_b32 s23, -1
	s_mov_b32 s22, 16
	s_branch .Lcv2_p0_ld
.Lcv2_p0_seg1:
	s_cmp_lt_u32 s4, 0xf00
	s_cbranch_scc0 .Lcv2_p0_seg2
	s_sub_u32 s34, s4, 0x400
	s_mul_i32 s39, s34, 5958
	s_lshr_b32 s39, s39, 19
	s_mul_i32 s40, s39, 88
	s_sub_u32 s40, s34, s40
	v_readlane_b32 s0, v234, 4
	v_readlane_b32 s1, v234, 5
	s_mul_i32 s2, s39, 0x160000
	s_lshl_b32 s3, s40, 8
	s_add_u32 s2, s2, s3
	s_add_u32 s0, s0, s2
	s_addc_u32 s1, s1, 0
	s_mov_b32 s41, 0x5800
	s_mov_b32 s42, 0x2c000
	s_lshr_b32 s2, s40, 1
	s_lshl_b32 s2, s2, 8
	s_and_b32 s3, s40, 1
	s_lshl_b32 s3, s3, 6
	s_add_u32 s2, s2, s3
	s_mul_i32 s2, s2, 0x1000
	s_lshl_b32 s3, s39, 7
	s_add_u32 s2, s2, s3
	s_add_u32 s2, s2, 0x8700000
	s_add_u32 s16, s30, s2
	s_addc_u32 s17, s31, 0
	s_mov_b32 s20, 0x1000
	s_mov_b32 s21, 0x4000
	s_mov_b32 s23, -1
	v_readlane_b32 s8, v233, 6
	v_readlane_b32 s9, v233, 7
	s_lshl_b32 s3, s39, 8
	s_mov_b32 s22, 18
	s_nop 0
	s_add_u32 s8, s8, s3
	s_addc_u32 s9, s9, 0
	s_branch .Lcv2_p0_ld
.Lcv2_p0_seg2:
	s_sub_u32 s34, s4, 0xf00
	s_mul_i32 s39, s34, 5958
	s_lshr_b32 s39, s39, 19
	s_mul_i32 s40, s39, 88
	s_sub_u32 s40, s34, s40
	v_readlane_b32 s0, v234, 6
	v_readlane_b32 s1, v234, 7
	s_mul_i32 s2, s39, 0x160000
	s_lshl_b32 s3, s40, 8
	s_add_u32 s2, s2, s3
	s_add_u32 s0, s0, s2
	s_addc_u32 s1, s1, 0
	s_mov_b32 s41, 0x5800
	s_mov_b32 s42, 0x2c000
	s_lshr_b32 s2, s40, 1
	s_lshl_b32 s2, s2, 8
	s_and_b32 s3, s40, 1
	s_lshl_b32 s3, s3, 6
	s_add_u32 s2, s2, s3
	s_add_u32 s2, s2, 0x80
	s_mul_i32 s2, s2, 0x1000
	s_lshl_b32 s3, s39, 7
	s_add_u32 s2, s2, s3
	s_add_u32 s2, s2, 0x8700000
	s_add_u32 s16, s30, s2
	s_addc_u32 s17, s31, 0
	s_mov_b32 s20, 0x1000
	s_mov_b32 s21, 0x4000
	s_mov_b32 s23, -1
	v_readlane_b32 s8, v233, 6
	v_readlane_b32 s9, v233, 7
	s_lshl_b32 s3, s39, 8
	s_mov_b32 s22, 18
	s_nop 0
	s_add_u32 s8, s8, s3
	s_addc_u32 s9, s9, 0

.Lcv2_p1_go:
	s_cmp_lt_u32 s4, 0x400
	s_cbranch_scc0 .Lcv2_p1_seg1
	s_add_u32 s34, s4, 0x0
	s_lshr_b32 s39, s34, 5
	s_and_b32 s40, s34, 31
	v_readlane_b32 s0, v233, 4
	v_readlane_b32 s1, v233, 5
	s_mul_i32 s2, s39, 0x80000
	s_lshl_b32 s3, s40, 8
	s_add_u32 s2, s2, s3
	s_add_u32 s0, s0, s2
	s_addc_u32 s1, s1, 0
	s_mov_b32 s41, 0x2000
	s_mov_b32 s42, 0x10000
	s_mul_i32 s2, s40, 0x40000
	s_lshl_b32 s3, s39, 7
	s_add_u32 s2, s2, s3
	s_add_u32 s2, s2, 0x7f00000
	s_add_u32 s24, s30, s2
	s_addc_u32 s25, s31, 0
	s_mov_b32 s26, 0x1000
	s_mov_b32 s27, 0x4000
	s_mov_b32 s29, -1
	s_mov_b32 s28, 16
	s_branch .Lcv2_p1_ld
.Lcv2_p1_seg1:
	s_cmp_lt_u32 s4, 0xf00
	s_cbranch_scc0 .Lcv2_p1_seg2
	s_sub_u32 s34, s4, 0x400
	s_mul_i32 s39, s34, 5958
	s_lshr_b32 s39, s39, 19
	s_mul_i32 s40, s39, 88
	s_sub_u32 s40, s34, s40
	v_readlane_b32 s0, v234, 4
	v_readlane_b32 s1, v234, 5
	s_mul_i32 s2, s39, 0x160000
	s_lshl_b32 s3, s40, 8
	s_add_u32 s2, s2, s3
	s_add_u32 s0, s0, s2
	s_addc_u32 s1, s1, 0
	s_mov_b32 s41, 0x5800
	s_mov_b32 s42, 0x2c000
	s_lshr_b32 s2, s40, 1
	s_lshl_b32 s2, s2, 8
	s_and_b32 s3, s40, 1
	s_lshl_b32 s3, s3, 6
	s_add_u32 s2, s2, s3
	s_mul_i32 s2, s2, 0x1000
	s_lshl_b32 s3, s39, 7
	s_add_u32 s2, s2, s3
	s_add_u32 s2, s2, 0x8700000
	s_add_u32 s24, s30, s2
	s_addc_u32 s25, s31, 0
	s_mov_b32 s26, 0x1000
	s_mov_b32 s27, 0x4000
	s_mov_b32 s29, -1
	v_readlane_b32 s8, v233, 6
	v_readlane_b32 s9, v233, 7
	s_lshl_b32 s3, s39, 8
	s_mov_b32 s28, 18
	s_nop 0
	s_add_u32 s8, s8, s3
	s_addc_u32 s9, s9, 0
	s_branch .Lcv2_p1_ld
.Lcv2_p1_seg2:
	s_sub_u32 s34, s4, 0xf00
	s_mul_i32 s39, s34, 5958
	s_lshr_b32 s39, s39, 19
	s_mul_i32 s40, s39, 88
	s_sub_u32 s40, s34, s40
	v_readlane_b32 s0, v234, 6
	v_readlane_b32 s1, v234, 7
	s_mul_i32 s2, s39, 0x160000
	s_lshl_b32 s3, s40, 8
	s_add_u32 s2, s2, s3
	s_add_u32 s0, s0, s2
	s_addc_u32 s1, s1, 0
	s_mov_b32 s41, 0x5800
	s_mov_b32 s42, 0x2c000
	s_lshr_b32 s2, s40, 1
	s_lshl_b32 s2, s2, 8
	s_and_b32 s3, s40, 1
	s_lshl_b32 s3, s3, 6
	s_add_u32 s2, s2, s3
	s_add_u32 s2, s2, 0x80
	s_mul_i32 s2, s2, 0x1000
	s_lshl_b32 s3, s39, 7
	s_add_u32 s2, s2, s3
	s_add_u32 s2, s2, 0x8700000
	s_add_u32 s24, s30, s2
	s_addc_u32 s25, s31, 0
	s_mov_b32 s26, 0x1000
	s_mov_b32 s27, 0x4000
	s_mov_b32 s29, -1
	v_readlane_b32 s8, v233, 6
	v_readlane_b32 s9, v233, 7
	s_lshl_b32 s3, s39, 8
	s_mov_b32 s28, 18
	s_nop 0
	s_add_u32 s8, s8, s3
	s_addc_u32 s9, s9, 0

.LBB0_2318:
	v_readlane_b32 s3, v234, 12
	s_movk_i32 s5, 0x5ac
.Lcv3_mod:
	s_cmp_ge_u32 s5, s3
	s_cbranch_scc0 .Lcv3_modd
	s_sub_u32 s5, s5, s3
	s_branch .Lcv3_mod
.Lcv3_modd:
	v_readlane_b32 s2, v234, 14
	s_cmp_eq_u32 s5, 0
	s_cbranch_scc1 .Lcv3_exit
	s_cmp_lt_i32 s2, s5
	s_cbranch_scc1 .Lcv3_exit
	v_readlane_b32 s2, v234, 14
	v_readlane_b32 s3, v234, 12
	v_readfirstlane_b32 s0, v183
	s_sub_i32 s2, s2, s5
	s_sub_i32 s3, s3, s5
	s_lshl_b32 s2, s2, 3
	s_lshr_b32 s0, s0, 6
	s_add_i32 s4, s2, s0
	s_lshl_b32 s33, s3, 3
	s_cmp_ge_u32 s4, 0xb00
	s_cbranch_scc1 .Lcv3_exit
	v_readlane_b32 s30, v234, 2
	v_readlane_b32 s31, v234, 3
	v_and_b32_e32 v220, 7, v183
	v_bfe_u32 v224, v183, 3, 3
	v_lshlrev_b32_e32 v221, 4, v224
	v_lshlrev_b32_e32 v225, 4, v220
	s_cmp_lt_u32 s4, 0xb00
	s_cbranch_scc1 .Lcv3_p0_go
	s_mov_b32 s22, 0
	s_branch .Lcv3_p0_end
.Lcv3_p0_go:
	s_add_u32 s34, s4, 0x0
	s_lshr_b32 s39, s34, 5
	s_and_b32 s40, s34, 31
	v_readlane_b32 s0, v234, 8
	v_readlane_b32 s1, v234, 9
	s_mul_i32 s2, s39, 0x80000
	s_lshl_b32 s3, s40, 8
	s_add_u32 s2, s2, s3
	s_add_u32 s0, s0, s2
	s_addc_u32 s1, s1, 0
	s_mov_b32 s41, 0x2000
	s_mov_b32 s42, 0x10000
	s_mul_i32 s2, s40, 0xb0000
	s_lshl_b32 s3, s39, 7
	s_add_u32 s2, s2, s3
	s_add_u32 s2, s2, 0xb300000
	s_add_u32 s16, s30, s2
	s_addc_u32 s17, s31, 0
	s_mov_b32 s20, 0x2c00
	s_mov_b32 s21, 0xb000
	s_mov_b32 s23, -1
	s_mov_b32 s22, 16
.Lcv3_p0_ld:
	v_mad_u32_u24 v222, v220, s42, v221
	global_load_dwordx4 v[0:3], v222, s[0:1] nt
	global_load_dwordx4 v[4:7], v222, s[0:1] offset:128 nt
	s_add_u32 s0, s0, s41
	s_addc_u32 s1, s1, 0
	global_load_dwordx4 v[8:11], v222, s[0:1] nt
	global_load_dwordx4 v[12:15], v222, s[0:1] offset:128 nt
	s_add_u32 s0, s0, s41
	s_addc_u32 s1, s1, 0
	global_load_dwordx4 v[16:19], v222, s[0:1] nt
	global_load_dwordx4 v[20:23], v222, s[0:1] offset:128 nt
	s_add_u32 s0, s0, s41
	s_addc_u32 s1, s1, 0
	global_load_dwordx4 v[24:27], v222, s[0:1] nt
	global_load_dwordx4 v[28:31], v222, s[0:1] offset:128 nt
	s_add_u32 s0, s0, s41
	s_addc_u32 s1, s1, 0
	global_load_dwordx4 v[32:35], v222, s[0:1] nt
	global_load_dwordx4 v[36:39], v222, s[0:1] offset:128 nt
	s_add_u32 s0, s0, s41
	s_addc_u32 s1, s1, 0
	global_load_dwordx4 v[40:43], v222, s[0:1] nt
	global_load_dwordx4 v[44:47], v222, s[0:1] offset:128 nt
	s_add_u32 s0, s0, s41
	s_addc_u32 s1, s1, 0
	global_load_dwordx4 v[48:51], v222, s[0:1] nt
	global_load_dwordx4 v[52:55], v222, s[0:1] offset:128 nt
	s_add_u32 s0, s0, s41
	s_addc_u32 s1, s1, 0
	global_load_dwordx4 v[56:59], v222, s[0:1] nt
	global_load_dwordx4 v[60:63], v222, s[0:1] offset:128 nt
.Lcv3_p0_kw:
	s_cmp_eq_u32 s22, 18
	s_cbranch_scc0 .Lcv3_p0_nokw
	v_lshlrev_b32_e32 v222, 5, v220
	global_load_dwordx4 v[128:131], v222, s[8:9]
	global_load_dwordx4 v[132:135], v222, s[8:9] offset:16
	s_branch .Lcv3_p0_kwd

.Lcv3_p0_end:
	s_cmp_lt_u32 s4, 0xb00
	s_cbranch_scc1 .Lcv3_p1_go
	s_mov_b32 s28, 0
	s_branch .Lcv3_p1_end
.Lcv3_p1_go:
	s_add_u32 s34, s4, 0x0
	s_lshr_b32 s39, s34, 5
	s_and_b32 s40, s34, 31
	v_readlane_b32 s0, v234, 8
	v_readlane_b32 s1, v234, 9
	s_mul_i32 s2, s39, 0x80000
	s_lshl_b32 s3, s40, 8
	s_add_u32 s2, s2, s3
	s_add_u32 s0, s0, s2
	s_addc_u32 s1, s1, 0
	s_mov_b32 s41, 0x2000
	s_mov_b32 s42, 0x10000
	s_mul_i32 s2, s40, 0xb0000
	s_lshl_b32 s3, s39, 7
	s_add_u32 s2, s2, s3
	s_add_u32 s2, s2, 0xb300000
	s_add_u32 s24, s30, s2
	s_addc_u32 s25, s31, 0
	s_mov_b32 s26, 0x2c00
	s_mov_b32 s27, 0xb000
	s_mov_b32 s29, -1
	s_mov_b32 s28, 16
.Lcv3_p1_ld:
	v_mad_u32_u24 v222, v220, s42, v221
	global_load_dwordx4 v[64:67], v222, s[0:1] nt
	global_load_dwordx4 v[68:71], v222, s[0:1] offset:128 nt
	s_add_u32 s0, s0, s41
	s_addc_u32 s1, s1, 0
	global_load_dwordx4 v[72:75], v222, s[0:1] nt
	global_load_dwordx4 v[76:79], v222, s[0:1] offset:128 nt
	s_add_u32 s0, s0, s41
	s_addc_u32 s1, s1, 0
	global_load_dwordx4 v[80:83], v222, s[0:1] nt
	global_load_dwordx4 v[84:87], v222, s[0:1] offset:128 nt
	s_add_u32 s0, s0, s41
	s_addc_u32 s1, s1, 0
	global_load_dwordx4 v[88:91], v222, s[0:1] nt
	global_load_dwordx4 v[92:95], v222, s[0:1] offset:128 nt
	s_add_u32 s0, s0, s41
	s_addc_u32 s1, s1, 0
	global_load_dwordx4 v[96:99], v222, s[0:1] nt
	global_load_dwordx4 v[100:103], v222, s[0:1] offset:128 nt
	s_add_u32 s0, s0, s41
	s_addc_u32 s1, s1, 0
	global_load_dwordx4 v[104:107], v222, s[0:1] nt
	global_load_dwordx4 v[108:111], v222, s[0:1] offset:128 nt
	s_add_u32 s0, s0, s41
	s_addc_u32 s1, s1, 0
	global_load_dwordx4 v[112:115], v222, s[0:1] nt
	global_load_dwordx4 v[116:119], v222, s[0:1] offset:128 nt
	s_add_u32 s0, s0, s41
	s_addc_u32 s1, s1, 0
	global_load_dwordx4 v[120:123], v222, s[0:1] nt
	global_load_dwordx4 v[124:127], v222, s[0:1] offset:128 nt
.Lcv3_p1_kw:
	s_cmp_eq_u32 s28, 18
	s_cbranch_scc0 .Lcv3_p1_nokw
	v_lshlrev_b32_e32 v222, 5, v220
	global_load_dwordx4 v[136:139], v222, s[8:9]
	global_load_dwordx4 v[140:143], v222, s[8:9] offset:16
	s_branch .Lcv3_p1_kwd

.Lcv3_pw_wd:
.Lcv3_loop:
	v_mad_u32_u24 v223, v224, s21, v225
	v_pk_mul_f32 v[0:1], v[0:1], v[128:129] op_sel_hi:[1,0]
	v_pk_mul_f32 v[2:3], v[2:3], v[128:129] op_sel_hi:[1,0]
	v_pk_mul_f32 v[4:5], v[4:5], v[128:129] op_sel_hi:[1,0]
	v_pk_mul_f32 v[6:7], v[6:7], v[128:129] op_sel_hi:[1,0]
	v_pk_mul_f32 v[8:9], v[8:9], v[128:129] op_sel:[0,1]
	v_pk_mul_f32 v[10:11], v[10:11], v[128:129] op_sel:[0,1]
	v_pk_mul_f32 v[12:13], v[12:13], v[128:129] op_sel:[0,1]
	v_pk_mul_f32 v[14:15], v[14:15], v[128:129] op_sel:[0,1]
	v_pk_mul_f32 v[16:17], v[16:17], v[130:131] op_sel_hi:[1,0]
	v_pk_mul_f32 v[18:19], v[18:19], v[130:131] op_sel_hi:[1,0]
	v_pk_mul_f32 v[20:21], v[20:21], v[130:131] op_sel_hi:[1,0]
	v_pk_mul_f32 v[22:23], v[22:23], v[130:131] op_sel_hi:[1,0]
	v_pk_mul_f32 v[24:25], v[24:25], v[130:131] op_sel:[0,1]
	v_pk_mul_f32 v[26:27], v[26:27], v[130:131] op_sel:[0,1]
	v_pk_mul_f32 v[28:29], v[28:29], v[130:131] op_sel:[0,1]
	v_pk_mul_f32 v[30:31], v[30:31], v[130:131] op_sel:[0,1]
	v_pk_mul_f32 v[32:33], v[32:33], v[132:133] op_sel_hi:[1,0]
	v_pk_mul_f32 v[34:35], v[34:35], v[132:133] op_sel_hi:[1,0]
	v_pk_mul_f32 v[36:37], v[36:37], v[132:133] op_sel_hi:[1,0]
	v_pk_mul_f32 v[38:39], v[38:39], v[132:133] op_sel_hi:[1,0]
	v_pk_mul_f32 v[40:41], v[40:41], v[132:133] op_sel:[0,1]
	v_pk_mul_f32 v[42:43], v[42:43], v[132:133] op_sel:[0,1]
	v_pk_mul_f32 v[44:45], v[44:45], v[132:133] op_sel:[0,1]
	v_pk_mul_f32 v[46:47], v[46:47], v[132:133] op_sel:[0,1]
	v_pk_mul_f32 v[48:49], v[48:49], v[134:135] op_sel_hi:[1,0]
	v_pk_mul_f32 v[50:51], v[50:51], v[134:135] op_sel_hi:[1,0]
	v_pk_mul_f32 v[52:53], v[52:53], v[134:135] op_sel_hi:[1,0]
	v_pk_mul_f32 v[54:55], v[54:55], v[134:135] op_sel_hi:[1,0]
	v_pk_mul_f32 v[56:57], v[56:57], v[134:135] op_sel:[0,1]
	v_pk_mul_f32 v[58:59], v[58:59], v[134:135] op_sel:[0,1]
	v_pk_mul_f32 v[60:61], v[60:61], v[134:135] op_sel:[0,1]
	v_pk_mul_f32 v[62:63], v[62:63], v[134:135] op_sel:[0,1]
	v_cvt_pk_bf16_f32 v188, v0, v8
	v_cvt_pk_bf16_f32 v189, v16, v24
	v_cvt_pk_bf16_f32 v190, v32, v40
	v_cvt_pk_bf16_f32 v191, v48, v56
	global_store_dwordx4 v223, v[188:191], s[16:17]
	v_cvt_pk_bf16_f32 v192, v1, v9
	v_cvt_pk_bf16_f32 v193, v17, v25
	v_cvt_pk_bf16_f32 v194, v33, v41
	v_cvt_pk_bf16_f32 v195, v49, v57
	s_add_u32 s16, s16, s20
	s_addc_u32 s17, s17, 0
	global_store_dwordx4 v223, v[192:195], s[16:17]
	v_cvt_pk_bf16_f32 v196, v2, v10
	v_cvt_pk_bf16_f32 v197, v18, v26
	v_cvt_pk_bf16_f32 v198, v34, v42
	v_cvt_pk_bf16_f32 v199, v50, v58
	s_add_u32 s16, s16, s20
	s_addc_u32 s17, s17, 0
	global_store_dwordx4 v223, v[196:199], s[16:17]
	v_cvt_pk_bf16_f32 v200, v3, v11
	v_cvt_pk_bf16_f32 v201, v19, v27
	v_cvt_pk_bf16_f32 v202, v35, v43
	v_cvt_pk_bf16_f32 v203, v51, v59
	s_add_u32 s16, s16, s20
	s_addc_u32 s17, s17, 0
	global_store_dwordx4 v223, v[200:203], s[16:17]
	v_cvt_pk_bf16_f32 v204, v4, v12
	v_cvt_pk_bf16_f32 v205, v20, v28
	v_cvt_pk_bf16_f32 v206, v36, v44
	v_cvt_pk_bf16_f32 v207, v52, v60
	s_mul_i32 s2, s20, 29
	s_add_u32 s16, s16, s2
	s_addc_u32 s17, s17, 0
	global_store_dwordx4 v223, v[204:207], s[16:17]
	v_cvt_pk_bf16_f32 v208, v5, v13
	v_cvt_pk_bf16_f32 v209, v21, v29
	v_cvt_pk_bf16_f32 v210, v37, v45
	v_cvt_pk_bf16_f32 v211, v53, v61
	s_add_u32 s16, s16, s20
	s_addc_u32 s17, s17, 0
	global_store_dwordx4 v223, v[208:211], s[16:17]
	v_cvt_pk_bf16_f32 v212, v6, v14
	v_cvt_pk_bf16_f32 v213, v22, v30
	v_cvt_pk_bf16_f32 v214, v38, v46
	v_cvt_pk_bf16_f32 v215, v54, v62
	s_add_u32 s16, s16, s20
	s_addc_u32 s17, s17, 0
	global_store_dwordx4 v223, v[212:215], s[16:17]
	v_cvt_pk_bf16_f32 v216, v7, v15
	v_cvt_pk_bf16_f32 v217, v23, v31
	v_cvt_pk_bf16_f32 v218, v39, v47
	v_cvt_pk_bf16_f32 v219, v55, v63
	s_add_u32 s16, s16, s20
	s_addc_u32 s17, s17, 0
	global_store_dwordx4 v223, v[216:219], s[16:17]
	s_cmp_lt_u32 s4, 0xb00
	s_cbranch_scc1 .Lcv3_la_go
	s_mov_b32 s22, 0
	s_branch .Lcv3_la_end

.Lcv3_wb_wd:
	v_mad_u32_u24 v223, v224, s27, v225
	v_pk_mul_f32 v[64:65], v[64:65], v[136:137] op_sel_hi:[1,0]
	v_pk_mul_f32 v[66:67], v[66:67], v[136:137] op_sel_hi:[1,0]
	v_pk_mul_f32 v[68:69], v[68:69], v[136:137] op_sel_hi:[1,0]
	v_pk_mul_f32 v[70:71], v[70:71], v[136:137] op_sel_hi:[1,0]
	v_pk_mul_f32 v[72:73], v[72:73], v[136:137] op_sel:[0,1]
	v_pk_mul_f32 v[74:75], v[74:75], v[136:137] op_sel:[0,1]
	v_pk_mul_f32 v[76:77], v[76:77], v[136:137] op_sel:[0,1]
	v_pk_mul_f32 v[78:79], v[78:79], v[136:137] op_sel:[0,1]
	v_pk_mul_f32 v[80:81], v[80:81], v[138:139] op_sel_hi:[1,0]
	v_pk_mul_f32 v[82:83], v[82:83], v[138:139] op_sel_hi:[1,0]
	v_pk_mul_f32 v[84:85], v[84:85], v[138:139] op_sel_hi:[1,0]
	v_pk_mul_f32 v[86:87], v[86:87], v[138:139] op_sel_hi:[1,0]
	v_pk_mul_f32 v[88:89], v[88:89], v[138:139] op_sel:[0,1]
	v_pk_mul_f32 v[90:91], v[90:91], v[138:139] op_sel:[0,1]
	v_pk_mul_f32 v[92:93], v[92:93], v[138:139] op_sel:[0,1]
	v_pk_mul_f32 v[94:95], v[94:95], v[138:139] op_sel:[0,1]
	v_pk_mul_f32 v[96:97], v[96:97], v[140:141] op_sel_hi:[1,0]
	v_pk_mul_f32 v[98:99], v[98:99], v[140:141] op_sel_hi:[1,0]
	v_pk_mul_f32 v[100:101], v[100:101], v[140:141] op_sel_hi:[1,0]
	v_pk_mul_f32 v[102:103], v[102:103], v[140:141] op_sel_hi:[1,0]
	v_pk_mul_f32 v[104:105], v[104:105], v[140:141] op_sel:[0,1]
	v_pk_mul_f32 v[106:107], v[106:107], v[140:141] op_sel:[0,1]
	v_pk_mul_f32 v[108:109], v[108:109], v[140:141] op_sel:[0,1]
	v_pk_mul_f32 v[110:111], v[110:111], v[140:141] op_sel:[0,1]
	v_pk_mul_f32 v[112:113], v[112:113], v[142:143] op_sel_hi:[1,0]
	v_pk_mul_f32 v[114:115], v[114:115], v[142:143] op_sel_hi:[1,0]
	v_pk_mul_f32 v[116:117], v[116:117], v[142:143] op_sel_hi:[1,0]
	v_pk_mul_f32 v[118:119], v[118:119], v[142:143] op_sel_hi:[1,0]
	v_pk_mul_f32 v[120:121], v[120:121], v[142:143] op_sel:[0,1]
	v_pk_mul_f32 v[122:123], v[122:123], v[142:143] op_sel:[0,1]
	v_pk_mul_f32 v[124:125], v[124:125], v[142:143] op_sel:[0,1]
	v_pk_mul_f32 v[126:127], v[126:127], v[142:143] op_sel:[0,1]
	v_cvt_pk_bf16_f32 v188, v64, v72
	v_cvt_pk_bf16_f32 v189, v80, v88
	v_cvt_pk_bf16_f32 v190, v96, v104
	v_cvt_pk_bf16_f32 v191, v112, v120
	global_store_dwordx4 v223, v[188:191], s[24:25]
	v_cvt_pk_bf16_f32 v192, v65, v73
	v_cvt_pk_bf16_f32 v193, v81, v89
	v_cvt_pk_bf16_f32 v194, v97, v105
	v_cvt_pk_bf16_f32 v195, v113, v121
	s_add_u32 s24, s24, s26
	s_addc_u32 s25, s25, 0
	global_store_dwordx4 v223, v[192:195], s[24:25]
	v_cvt_pk_bf16_f32 v196, v66, v74
	v_cvt_pk_bf16_f32 v197, v82, v90
	v_cvt_pk_bf16_f32 v198, v98, v106
	v_cvt_pk_bf16_f32 v199, v114, v122
	s_add_u32 s24, s24, s26
	s_addc_u32 s25, s25, 0
	global_store_dwordx4 v223, v[196:199], s[24:25]
	v_cvt_pk_bf16_f32 v200, v67, v75
	v_cvt_pk_bf16_f32 v201, v83, v91
	v_cvt_pk_bf16_f32 v202, v99, v107
	v_cvt_pk_bf16_f32 v203, v115, v123
	s_add_u32 s24, s24, s26
	s_addc_u32 s25, s25, 0
	global_store_dwordx4 v223, v[200:203], s[24:25]
	v_cvt_pk_bf16_f32 v204, v68, v76
	v_cvt_pk_bf16_f32 v205, v84, v92
	v_cvt_pk_bf16_f32 v206, v100, v108
	v_cvt_pk_bf16_f32 v207, v116, v124
	s_mul_i32 s2, s26, 29
	s_add_u32 s24, s24, s2
	s_addc_u32 s25, s25, 0
	global_store_dwordx4 v223, v[204:207], s[24:25]
	v_cvt_pk_bf16_f32 v208, v69, v77
	v_cvt_pk_bf16_f32 v209, v85, v93
	v_cvt_pk_bf16_f32 v210, v101, v109
	v_cvt_pk_bf16_f32 v211, v117, v125
	s_add_u32 s24, s24, s26
	s_addc_u32 s25, s25, 0
	global_store_dwordx4 v223, v[208:211], s[24:25]
	v_cvt_pk_bf16_f32 v212, v70, v78
	v_cvt_pk_bf16_f32 v213, v86, v94
	v_cvt_pk_bf16_f32 v214, v102, v110
	v_cvt_pk_bf16_f32 v215, v118, v126
	s_add_u32 s24, s24, s26
	s_addc_u32 s25, s25, 0
	global_store_dwordx4 v223, v[212:215], s[24:25]
	v_cvt_pk_bf16_f32 v216, v71, v79
	v_cvt_pk_bf16_f32 v217, v87, v95
	v_cvt_pk_bf16_f32 v218, v103, v111
	v_cvt_pk_bf16_f32 v219, v119, v127
	s_add_u32 s24, s24, s26
	s_addc_u32 s25, s25, 0
	global_store_dwordx4 v223, v[216:219], s[24:25]
	s_cmp_lt_u32 s4, 0xb00
	s_cbranch_scc1 .Lcv3_lb_go
	s_mov_b32 s28, 0
	s_branch .Lcv3_lb_end

.Lcv3_done:
.Lcv3_exit:
	s_waitcnt vmcnt(0)
	s_barrier
	s_mov_b64 s[0:1], exec
	v_readlane_b32 s2, v234, 20
	v_readlane_b32 s3, v234, 21
	s_and_b64 s[2:3], s[0:1], s[2:3]
	s_mov_b64 exec, s[2:3]
	s_cbranch_execz .LBB0_2370
	s_add_i32 s2, 0, 0x27ff0
	v_mov_b32_e32 v0, s2
	s_waitcnt vmcnt(0) expcnt(0) lgkmcnt(0)
	ds_read_b32 v2, v0
	s_add_i32 s2, 0, 0x27ff4
	v_mov_b32_e32 v0, s2
	ds_read_b32 v0, v0
	s_waitcnt lgkmcnt(1)
	v_cmp_ne_u32_e32 vcc, 0, v2
	s_cbranch_vccnz .LBB0_2334
	v_readlane_b32 s2, v234, 12
	v_readlane_b32 s3, v234, 13
	v_readlane_b32 s4, v234, 16
	v_readlane_b32 s36, v234, 0
	s_mul_i32 s33, s3, s4
	v_readlane_b32 s38, v234, 2
	s_mul_i32 s33, s33, s2
	v_readlane_b32 s39, v234, 3
	s_add_u32 s2, s38, 0x100200
	s_addc_u32 s3, s39, 0
	s_add_u32 s4, s38, 0x100400
	s_addc_u32 s5, s39, 0
	s_add_u32 s6, s38, 0x100500
	s_addc_u32 s7, s39, 0
	s_add_u32 s8, s38, 0x100600
	s_addc_u32 s9, s39, 0
	s_add_u32 s10, s38, 0x100700
	s_addc_u32 s11, s39, 0
	s_add_u32 s12, s38, 0x100800
	s_addc_u32 s13, s39, 0
	s_add_u32 s14, s38, 0x100900
	s_addc_u32 s15, s39, 0
	s_add_u32 s16, s38, 0x100a00
	s_addc_u32 s17, s39, 0
	s_add_u32 s18, s38, 0x100b00
	s_addc_u32 s19, s39, 0
	s_add_u32 s20, s38, 0x100c00
	s_addc_u32 s21, s39, 0
	s_add_u32 s22, s38, 0x100d00
	s_addc_u32 s23, s39, 0
	s_add_u32 s24, s38, 0x100e00
	s_addc_u32 s25, s39, 0
	s_add_u32 s26, s38, 0x100f00
	s_addc_u32 s27, s39, 0
	s_add_u32 s28, s38, 0x101000
	s_addc_u32 s29, s39, 0
	s_add_u32 s30, s38, 0x101100
	s_addc_u32 s31, s39, 0
	s_add_u32 s34, s38, 0x101200
	s_addc_u32 s35, s39, 0
	v_readlane_b32 s37, v234, 1
	s_add_u32 s36, s38, 0x101300
	s_addc_u32 s37, s39, 0
	s_mov_b32 s44, 1
	v_mov_b32_e32 v16, 0
	s_branch .LBB0_2322
